# hand-written P3 residual epilogue (f32 residual, three row groups in flight, one LDS transpose per output, parameters up front)
# speedup vs baseline: 1.0035x; 1.0035x over previous
; #define PG8_LAS __attribute__((address_space(3)))
; __device__ __forceinline__ u32x4 pack8(const f32x4 a, const f32x4 b) { u32x4 w; w.x = cvt_pk_bf16(a[0], a[1]); w.y = cvt_pk_bf16(a[2], a[3]); w.z = cvt_pk_bf16(b[0], b[1]); w.w = cvt_pk_bf16(b[2], b[3]); return w; }
;     __device__ __forceinline__ void operator()(const f32x4 (&acc)[2][2][4][2], const Unit& u, int wr, int wc, int fr, int fq) const {
;         asm volatile("" : "+v"(fr), "+v"(fq));
;         const int b = u.pm >> 5, col0 = u.pn * BM + wc * 64 + fq * 8;
;         PG8_LAS unsigned char* st = stg + (wr * 4 + wc) * 1024;
;         f32x4 gv[2][2], cs[2][2];
; #pragma unroll
;         for (int bj = 0; bj < 2; ++bj)
; #pragma unroll
;             for (int n = 0; n < 2; ++n) { const int c = col0 + bj * 32 + 4 * n; gv[bj][n] = *(const f32x4*)(gate + (size_t)b * NMODC + c) * (HALFG ? 0.5f : 1.0f);
;                 cs[bj][n] = (f32x4){0.f, 0.f, 0.f, 0.f}; if (XS) cs[bj][n] = *(const f32x4*)(gcol + c) * (*(const f32x4*)(scm + (size_t)b * NMODC + c) + 1.0f); }
;         u32x4 c16[2], n16[2]; f32x4 c32[2][2], n32[2][2];
;     ...
;         RES_LOAD(c16, c32, 0);
; #pragma unroll
;         for (int r = 0; r < 8; ++r) { const int ai = r >> 2, m = r & 3; const int row = EPI_ROW; float sq = 0.f;
;             if (r < 7) RES_LOAD(n16, n32, r + 1);
;             u32x4 pn_[2], ps_[2];
; #pragma unroll
;             for (int bj = 0; bj < 2; ++bj) {
;                 f32x4 o0, o1;
;                 if (XOLD16) unpack8(c16[bj], o0, o1); else { o0 = c32[bj][0]; o1 = c32[bj][1]; }
;                 const f32x4 v0 = o0 + gv[bj][0] * acc[ai][bj][m][0], v1 = o1 + gv[bj][1] * acc[ai][bj][m][1];
;                 pn_[bj] = pack8(v0, v1);
;                 sq += ((v0[0] * v0[0] + v0[1] * v0[1]) + (v0[2] * v0[2] + v0[3] * v0[3])) + ((v1[0] * v1[0] + v1[1] * v1[1]) + (v1[2] * v1[2] + v1[3] * v1[3]));
;                 if (XS) ps_[bj] = pack8(v0 * cs[bj][0], v1 * cs[bj][1]); }
.LBB0_292:
	s_mov_b32 s98, s38
	s_lshl_b32 s1, s16, 8
	s_or_b32 s1, s1, s28
	s_lshl_b32 s4, s98, 8
	s_add_i32 s4, s4, s62
	s_ashr_i32 s5, s98, 5
	s_mul_i32 s5, s5, 0x9000
	s_lshl_b32 s6, s1, 2
	s_add_u32 s5, s5, s6
	s_add_u32 s36, s55, s5
	s_addc_u32 s37, s56, 0
	s_add_u32 s38, s59, s5
	s_addc_u32 s39, s60, 0
	s_add_u32 s40, s14, s6
	s_addc_u32 s41, s15, 0
	v_lshlrev_b32_e32 v247, 5, v221
	global_load_dwordx4 v[172:175], v247, s[36:37]
	global_load_dwordx4 v[168:171], v247, s[36:37] offset:16
	global_load_dwordx4 v[164:167], v247, s[36:37] offset:128
	global_load_dwordx4 v[160:163], v247, s[36:37] offset:144
	global_load_dwordx4 v[188:191], v247, s[38:39]
	global_load_dwordx4 v[184:187], v247, s[38:39] offset:16
	global_load_dwordx4 v[180:183], v247, s[38:39] offset:128
	global_load_dwordx4 v[176:179], v247, s[38:39] offset:144
	global_load_dwordx4 v[142:145], v247, s[40:41]
	global_load_dwordx4 v[138:141], v247, s[40:41] offset:16
	global_load_dwordx4 v[134:137], v247, s[40:41] offset:128
	global_load_dwordx4 v[130:133], v247, s[40:41] offset:144
	s_lshl_b32 s5, s4, 12
	s_lshl_b32 s6, s1, 2
	s_add_u32 s5, s5, s6
	s_add_u32 s36, s10, s5
	s_addc_u32 s37, s11, 0
	s_lshl_b32 s5, s4, 11
	s_lshl_b32 s6, s1, 1
	s_add_u32 s5, s5, s6
	s_add_u32 s38, s12, s5
	s_addc_u32 s39, s13, 0
	s_add_u32 s40, s57, s5
	s_addc_u32 s41, s58, 0
	v_lshlrev_b32_e32 v248, 12, v1
	v_lshl_add_u32 v248, v221, 5, v248
	global_load_dwordx4 v[204:207], v248, s[36:37]
	global_load_dwordx4 v[200:203], v248, s[36:37] offset:16
	global_load_dwordx4 v[196:199], v248, s[36:37] offset:128
	global_load_dwordx4 v[192:195], v248, s[36:37] offset:144
	s_add_u32 s36, s36, 0x10000
	s_addc_u32 s37, s37, 0
	global_load_dwordx4 v[238:241], v248, s[36:37]
	global_load_dwordx4 v[234:237], v248, s[36:37] offset:16
	global_load_dwordx4 v[230:233], v248, s[36:37] offset:128
	global_load_dwordx4 v[226:229], v248, s[36:37] offset:144
	s_add_u32 s36, s36, 0x10000
	s_addc_u32 s37, s37, 0
	v_lshlrev_b32_e32 v249, 6, v1
	s_lshl_b32 s5, s62, 7
	s_lshl_b32 s6, s61, 11
	s_add_i32 s5, s5, s6
	s_add_i32 s5, s5, 0x20000
	v_lshlrev_b32_e32 v250, 7, v1
	v_lshl_add_u32 v250, v221, 4, v250
	v_add_u32_e32 v250, s5, v250
	v_lshl_add_u32 v251, v220, 4, s5
	v_lshrrev_b32_e32 v255, 3, v220
	v_lshlrev_b32_e32 v255, 11, v255
	v_and_b32_e32 v216, 7, v220
	v_lshl_add_u32 v255, v216, 4, v255
	s_waitcnt vmcnt(8)
	v_pk_mul_f32 v[160:161], v[160:161], 0.5 op_sel_hi:[1,0]
	v_pk_mul_f32 v[162:163], v[162:163], 0.5 op_sel_hi:[1,0]
	v_pk_mul_f32 v[164:165], v[164:165], 0.5 op_sel_hi:[1,0]
	v_pk_mul_f32 v[166:167], v[166:167], 0.5 op_sel_hi:[1,0]
	v_pk_mul_f32 v[168:169], v[168:169], 0.5 op_sel_hi:[1,0]
	v_pk_mul_f32 v[170:171], v[170:171], 0.5 op_sel_hi:[1,0]
	v_pk_mul_f32 v[172:173], v[172:173], 0.5 op_sel_hi:[1,0]
	v_pk_mul_f32 v[174:175], v[174:175], 0.5 op_sel_hi:[1,0]
	v_pk_add_f32 v[176:177], v[176:177], 1.0 op_sel_hi:[1,0]
	v_pk_add_f32 v[178:179], v[178:179], 1.0 op_sel_hi:[1,0]
	v_pk_add_f32 v[180:181], v[180:181], 1.0 op_sel_hi:[1,0]
	v_pk_add_f32 v[182:183], v[182:183], 1.0 op_sel_hi:[1,0]
	v_pk_add_f32 v[184:185], v[184:185], 1.0 op_sel_hi:[1,0]
	v_pk_add_f32 v[186:187], v[186:187], 1.0 op_sel_hi:[1,0]
	v_pk_add_f32 v[188:189], v[188:189], 1.0 op_sel_hi:[1,0]
	v_pk_add_f32 v[190:191], v[190:191], 1.0 op_sel_hi:[1,0]
	v_pk_mul_f32 v[176:177], v[130:131], v[176:177]
	v_pk_mul_f32 v[178:179], v[132:133], v[178:179]
	v_pk_mul_f32 v[180:181], v[134:135], v[180:181]
	v_pk_mul_f32 v[182:183], v[136:137], v[182:183]
	v_pk_mul_f32 v[184:185], v[138:139], v[184:185]
	v_pk_mul_f32 v[186:187], v[140:141], v[186:187]
	v_pk_mul_f32 v[188:189], v[142:143], v[188:189]
	v_pk_mul_f32 v[190:191], v[144:145], v[190:191]
	global_load_dwordx4 v[142:145], v248, s[36:37]
	global_load_dwordx4 v[138:141], v248, s[36:37] offset:16
	global_load_dwordx4 v[134:137], v248, s[36:37] offset:128
	global_load_dwordx4 v[130:133], v248, s[36:37] offset:144
	s_add_u32 s36, s36, 0x10000
	s_addc_u32 s37, s37, 0
	s_waitcnt vmcnt(8)
	v_pk_fma_f32 v[126:127], v[126:127], v[172:173], v[204:205]
	v_pk_fma_f32 v[128:129], v[128:129], v[174:175], v[206:207]
	v_pk_fma_f32 v[122:123], v[122:123], v[168:169], v[200:201]
	v_pk_fma_f32 v[124:125], v[124:125], v[170:171], v[202:203]
	v_pk_fma_f32 v[118:119], v[118:119], v[164:165], v[196:197]
	v_pk_fma_f32 v[120:121], v[120:121], v[166:167], v[198:199]
	v_pk_fma_f32 v[114:115], v[114:115], v[160:161], v[192:193]
	v_pk_fma_f32 v[116:117], v[116:117], v[162:163], v[194:195]
	global_load_dwordx4 v[204:207], v248, s[36:37]
	global_load_dwordx4 v[200:203], v248, s[36:37] offset:16
	global_load_dwordx4 v[196:199], v248, s[36:37] offset:128
	global_load_dwordx4 v[192:195], v248, s[36:37] offset:144
	s_add_u32 s36, s36, 0x50000
	s_addc_u32 s37, s37, 0
	v_mul_f32_e32 v216, v127, v127
	v_mul_f32_e32 v217, v129, v129
	v_fmac_f32_e32 v216, v126, v126
	v_fmac_f32_e32 v217, v128, v128
	v_add_f32_e32 v216, v216, v217
	v_mul_f32_e32 v217, v123, v123
	v_mul_f32_e32 v218, v125, v125
	v_fmac_f32_e32 v217, v122, v122
	v_fmac_f32_e32 v218, v124, v124
	v_add_f32_e32 v217, v217, v218
	v_add_f32_e32 v216, v216, v217
	v_mul_f32_e32 v217, v119, v119
	v_mul_f32_e32 v218, v121, v121
	v_fmac_f32_e32 v217, v118, v118
	v_fmac_f32_e32 v218, v120, v120
	v_add_f32_e32 v217, v217, v218
	v_mul_f32_e32 v218, v115, v115
	v_mul_f32_e32 v219, v117, v117
	v_fmac_f32_e32 v218, v114, v114
	v_fmac_f32_e32 v219, v116, v116
	v_add_f32_e32 v218, v218, v219
	v_add_f32_e32 v217, v217, v218
	v_add_f32_e32 v246, v216, v217
	v_cvt_pk_bf16_f32 v208, v126, v127
	v_cvt_pk_bf16_f32 v209, v128, v129
	v_cvt_pk_bf16_f32 v210, v122, v123
	v_cvt_pk_bf16_f32 v211, v124, v125
	v_cvt_pk_bf16_f32 v212, v118, v119
	v_cvt_pk_bf16_f32 v213, v120, v121
	v_cvt_pk_bf16_f32 v214, v114, v115
	v_cvt_pk_bf16_f32 v215, v116, v117
	ds_write_b128 v250, v[208:211]
	ds_write_b128 v250, v[212:215] offset:64
	ds_read_b128 v[216:219], v251
	ds_read_b128 v[242:245], v251 offset:1024
	s_add_u32 s4, s38, 0x4000
	s_addc_u32 s5, s39, 0
	s_waitcnt lgkmcnt(1)
; __device__ __forceinline__ u32x4 pack8(const f32x4 a, const f32x4 b) { u32x4 w; w.x = cvt_pk_bf16(a[0], a[1]); w.y = cvt_pk_bf16(a[2], a[3]); w.z = cvt_pk_bf16(b[0], b[1]); w.w = cvt_pk_bf16(b[2], b[3]); return w; }
;     __device__ __forceinline__ void operator()(const f32x4 (&acc)[2][2][4][2], const Unit& u, int wr, int wc, int fr, int fq) const {
;     ...
;         for (int r = 0; r < 8; ++r) { const int ai = r >> 2, m = r & 3; const int row = EPI_ROW; float sq = 0.f;
;             if (r < 7) RES_LOAD(n16, n32, r + 1);
;             u32x4 pn_[2], ps_[2];
; #pragma unroll
;             for (int bj = 0; bj < 2; ++bj) {
;                 f32x4 o0, o1;
;                 if (XOLD16) unpack8(c16[bj], o0, o1); else { o0 = c32[bj][0]; o1 = c32[bj][1]; }
;                 const f32x4 v0 = o0 + gv[bj][0] * acc[ai][bj][m][0], v1 = o1 + gv[bj][1] * acc[ai][bj][m][1];
;                 pn_[bj] = pack8(v0, v1);
;                 sq += ((v0[0] * v0[0] + v0[1] * v0[1]) + (v0[2] * v0[2] + v0[3] * v0[3])) + ((v1[0] * v1[0] + v1[1] * v1[1]) + (v1[2] * v1[2] + v1[3] * v1[3]));
;                 if (XS) ps_[bj] = pack8(v0 * cs[bj][0], v1 * cs[bj][1]); }
;             { const size_t seg = (size_t)(row - fr) * DM + u.pn * BM + wc * 64;
;               store_lines(st, pn_[0], pn_[1], fr, fq, xnew + seg, DM);
;               if (XS) store_lines(st, ps_[0], ps_[1], fr, fq, xs + seg, DM); }
;             sq += __shfl_xor(sq, 16); sq += __shfl_xor(sq, 32);
;             if (fq == 0) ssq[(size_t)row * 16 + u.pn * 4 + wc] = sq;
; #pragma unroll
;             for (int bj = 0; bj < 2; ++bj) { c16[bj] = n16[bj]; c32[bj][0] = n32[bj][0]; c32[bj][1] = n32[bj][1]; } }
	global_store_dwordx4 v255, v[216:219], s[38:39]
	s_waitcnt lgkmcnt(0)
	global_store_dwordx4 v255, v[242:245], s[4:5]
	v_pk_mul_f32 v[126:127], v[188:189], v[126:127]
	v_pk_mul_f32 v[128:129], v[190:191], v[128:129]
	v_pk_mul_f32 v[122:123], v[184:185], v[122:123]
	v_pk_mul_f32 v[124:125], v[186:187], v[124:125]
	v_pk_mul_f32 v[118:119], v[180:181], v[118:119]
	v_pk_mul_f32 v[120:121], v[182:183], v[120:121]
	v_pk_mul_f32 v[114:115], v[176:177], v[114:115]
	v_pk_mul_f32 v[116:117], v[178:179], v[116:117]
	v_cvt_pk_bf16_f32 v208, v126, v127
	v_cvt_pk_bf16_f32 v209, v128, v129
	v_cvt_pk_bf16_f32 v210, v122, v123
	v_cvt_pk_bf16_f32 v211, v124, v125
	v_cvt_pk_bf16_f32 v212, v118, v119
	v_cvt_pk_bf16_f32 v213, v120, v121
	v_cvt_pk_bf16_f32 v214, v114, v115
	v_cvt_pk_bf16_f32 v215, v116, v117
	v_mov_b32_e32 v114, v246
	ds_write_b128 v250, v[208:211]
	ds_write_b128 v250, v[212:215] offset:64
	ds_read_b128 v[216:219], v251
	ds_read_b128 v[242:245], v251 offset:1024
	s_add_u32 s4, s40, 0x4000
	s_addc_u32 s5, s41, 0
	s_waitcnt lgkmcnt(1)
	global_store_dwordx4 v255, v[216:219], s[40:41]
	s_waitcnt lgkmcnt(0)
	global_store_dwordx4 v255, v[242:245], s[4:5]
	s_add_u32 s38, s38, 0x8000
	s_addc_u32 s39, s39, 0
	s_add_u32 s40, s40, 0x8000
	s_addc_u32 s41, s41, 0
	s_waitcnt vmcnt(12)
	v_pk_fma_f32 v[110:111], v[110:111], v[172:173], v[238:239]
	v_pk_fma_f32 v[112:113], v[112:113], v[174:175], v[240:241]
	v_pk_fma_f32 v[106:107], v[106:107], v[168:169], v[234:235]
	v_pk_fma_f32 v[108:109], v[108:109], v[170:171], v[236:237]
	v_pk_fma_f32 v[102:103], v[102:103], v[164:165], v[230:231]
	v_pk_fma_f32 v[104:105], v[104:105], v[166:167], v[232:233]
	v_pk_fma_f32 v[98:99], v[98:99], v[160:161], v[226:227]
	v_pk_fma_f32 v[100:101], v[100:101], v[162:163], v[228:229]
	global_load_dwordx4 v[238:241], v248, s[36:37]
	global_load_dwordx4 v[234:237], v248, s[36:37] offset:16
	global_load_dwordx4 v[230:233], v248, s[36:37] offset:128
	global_load_dwordx4 v[226:229], v248, s[36:37] offset:144
	s_add_u32 s36, s36, 0x10000
	s_addc_u32 s37, s37, 0
	v_mul_f32_e32 v216, v111, v111
	v_mul_f32_e32 v217, v113, v113
	v_fmac_f32_e32 v216, v110, v110
	v_fmac_f32_e32 v217, v112, v112
	v_add_f32_e32 v216, v216, v217
	v_mul_f32_e32 v217, v107, v107
	v_mul_f32_e32 v218, v109, v109
	v_fmac_f32_e32 v217, v106, v106
	v_fmac_f32_e32 v218, v108, v108
	v_add_f32_e32 v217, v217, v218
	v_add_f32_e32 v216, v216, v217
	v_mul_f32_e32 v217, v103, v103
	v_mul_f32_e32 v218, v105, v105
	v_fmac_f32_e32 v217, v102, v102
	v_fmac_f32_e32 v218, v104, v104
	v_add_f32_e32 v217, v217, v218
	v_mul_f32_e32 v218, v99, v99
	v_mul_f32_e32 v219, v101, v101
	v_fmac_f32_e32 v218, v98, v98
	v_fmac_f32_e32 v219, v100, v100
	v_add_f32_e32 v218, v218, v219
	v_add_f32_e32 v217, v217, v218
	v_add_f32_e32 v246, v216, v217
	v_cvt_pk_bf16_f32 v208, v110, v111
	v_cvt_pk_bf16_f32 v209, v112, v113
	v_cvt_pk_bf16_f32 v210, v106, v107
	v_cvt_pk_bf16_f32 v211, v108, v109
	v_cvt_pk_bf16_f32 v212, v102, v103
	v_cvt_pk_bf16_f32 v213, v104, v105
	v_cvt_pk_bf16_f32 v214, v98, v99
	v_cvt_pk_bf16_f32 v215, v100, v101
	ds_write_b128 v250, v[208:211]
	ds_write_b128 v250, v[212:215] offset:64
	ds_read_b128 v[216:219], v251
	ds_read_b128 v[242:245], v251 offset:1024
	s_add_u32 s4, s38, 0x4000
	s_addc_u32 s5, s39, 0
	s_waitcnt lgkmcnt(1)
	global_store_dwordx4 v255, v[216:219], s[38:39]
	s_waitcnt lgkmcnt(0)
	global_store_dwordx4 v255, v[242:245], s[4:5]
	v_pk_mul_f32 v[110:111], v[188:189], v[110:111]
	v_pk_mul_f32 v[112:113], v[190:191], v[112:113]
	v_pk_mul_f32 v[106:107], v[184:185], v[106:107]
	v_pk_mul_f32 v[108:109], v[186:187], v[108:109]
	v_pk_mul_f32 v[102:103], v[180:181], v[102:103]
	v_pk_mul_f32 v[104:105], v[182:183], v[104:105]
	v_pk_mul_f32 v[98:99], v[176:177], v[98:99]
	v_pk_mul_f32 v[100:101], v[178:179], v[100:101]
	v_cvt_pk_bf16_f32 v208, v110, v111
	v_cvt_pk_bf16_f32 v209, v112, v113
	v_cvt_pk_bf16_f32 v210, v106, v107
	v_cvt_pk_bf16_f32 v211, v108, v109
	v_cvt_pk_bf16_f32 v212, v102, v103
	v_cvt_pk_bf16_f32 v213, v104, v105
	v_cvt_pk_bf16_f32 v214, v98, v99
	v_cvt_pk_bf16_f32 v215, v100, v101
	v_mov_b32_e32 v98, v246
	ds_write_b128 v250, v[208:211]
	ds_write_b128 v250, v[212:215] offset:64
	ds_read_b128 v[216:219], v251
	ds_read_b128 v[242:245], v251 offset:1024
	s_add_u32 s4, s40, 0x4000
	s_addc_u32 s5, s41, 0
	s_waitcnt lgkmcnt(1)
	global_store_dwordx4 v255, v[216:219], s[40:41]
	s_waitcnt lgkmcnt(0)
	global_store_dwordx4 v255, v[242:245], s[4:5]
	s_add_u32 s38, s38, 0x8000
	s_addc_u32 s39, s39, 0
	s_add_u32 s40, s40, 0x8000
	s_addc_u32 s41, s41, 0
	s_waitcnt vmcnt(16)
	v_pk_fma_f32 v[94:95], v[94:95], v[172:173], v[142:143]
	v_pk_fma_f32 v[96:97], v[96:97], v[174:175], v[144:145]
	v_pk_fma_f32 v[90:91], v[90:91], v[168:169], v[138:139]
	v_pk_fma_f32 v[92:93], v[92:93], v[170:171], v[140:141]
	v_pk_fma_f32 v[86:87], v[86:87], v[164:165], v[134:135]
	v_pk_fma_f32 v[88:89], v[88:89], v[166:167], v[136:137]
	v_pk_fma_f32 v[82:83], v[82:83], v[160:161], v[130:131]
	v_pk_fma_f32 v[84:85], v[84:85], v[162:163], v[132:133]
	global_load_dwordx4 v[142:145], v248, s[36:37]
	global_load_dwordx4 v[138:141], v248, s[36:37] offset:16
	global_load_dwordx4 v[134:137], v248, s[36:37] offset:128
	global_load_dwordx4 v[130:133], v248, s[36:37] offset:144
	s_add_u32 s36, s36, 0x10000
	s_addc_u32 s37, s37, 0
	v_mul_f32_e32 v216, v95, v95
	v_mul_f32_e32 v217, v97, v97
	v_fmac_f32_e32 v216, v94, v94
	v_fmac_f32_e32 v217, v96, v96
	v_add_f32_e32 v216, v216, v217
	v_mul_f32_e32 v217, v91, v91
	v_mul_f32_e32 v218, v93, v93
	v_fmac_f32_e32 v217, v90, v90
	v_fmac_f32_e32 v218, v92, v92
	v_add_f32_e32 v217, v217, v218
	v_add_f32_e32 v216, v216, v217
	v_mul_f32_e32 v217, v87, v87
	v_mul_f32_e32 v218, v89, v89
	v_fmac_f32_e32 v217, v86, v86
	v_fmac_f32_e32 v218, v88, v88
	v_add_f32_e32 v217, v217, v218
	v_mul_f32_e32 v218, v83, v83
	v_mul_f32_e32 v219, v85, v85
	v_fmac_f32_e32 v218, v82, v82
	v_fmac_f32_e32 v219, v84, v84
	v_add_f32_e32 v218, v218, v219
	v_add_f32_e32 v217, v217, v218
	v_add_f32_e32 v246, v216, v217
	v_cvt_pk_bf16_f32 v208, v94, v95
	v_cvt_pk_bf16_f32 v209, v96, v97
	v_cvt_pk_bf16_f32 v210, v90, v91
	v_cvt_pk_bf16_f32 v211, v92, v93
	v_cvt_pk_bf16_f32 v212, v86, v87
	v_cvt_pk_bf16_f32 v213, v88, v89
	v_cvt_pk_bf16_f32 v214, v82, v83
	v_cvt_pk_bf16_f32 v215, v84, v85
	ds_write_b128 v250, v[208:211]
	ds_write_b128 v250, v[212:215] offset:64
	ds_read_b128 v[216:219], v251
	ds_read_b128 v[242:245], v251 offset:1024
	s_add_u32 s4, s38, 0x4000
	s_addc_u32 s5, s39, 0
	s_waitcnt lgkmcnt(1)
; __device__ __forceinline__ u32x4 pack8(const f32x4 a, const f32x4 b) { u32x4 w; w.x = cvt_pk_bf16(a[0], a[1]); w.y = cvt_pk_bf16(a[2], a[3]); w.z = cvt_pk_bf16(b[0], b[1]); w.w = cvt_pk_bf16(b[2], b[3]); return w; }
;     __device__ __forceinline__ void operator()(const f32x4 (&acc)[2][2][4][2], const Unit& u, int wr, int wc, int fr, int fq) const {
;     ...
;         for (int r = 0; r < 8; ++r) { const int ai = r >> 2, m = r & 3; const int row = EPI_ROW; float sq = 0.f;
;             if (r < 7) RES_LOAD(n16, n32, r + 1);
;             u32x4 pn_[2], ps_[2];
; #pragma unroll
;             for (int bj = 0; bj < 2; ++bj) {
;                 f32x4 o0, o1;
;                 if (XOLD16) unpack8(c16[bj], o0, o1); else { o0 = c32[bj][0]; o1 = c32[bj][1]; }
;                 const f32x4 v0 = o0 + gv[bj][0] * acc[ai][bj][m][0], v1 = o1 + gv[bj][1] * acc[ai][bj][m][1];
;                 pn_[bj] = pack8(v0, v1);
;                 sq += ((v0[0] * v0[0] + v0[1] * v0[1]) + (v0[2] * v0[2] + v0[3] * v0[3])) + ((v1[0] * v1[0] + v1[1] * v1[1]) + (v1[2] * v1[2] + v1[3] * v1[3]));
;                 if (XS) ps_[bj] = pack8(v0 * cs[bj][0], v1 * cs[bj][1]); }
;             { const size_t seg = (size_t)(row - fr) * DM + u.pn * BM + wc * 64;
;               store_lines(st, pn_[0], pn_[1], fr, fq, xnew + seg, DM);
;               if (XS) store_lines(st, ps_[0], ps_[1], fr, fq, xs + seg, DM); }
;             sq += __shfl_xor(sq, 16); sq += __shfl_xor(sq, 32);
;             if (fq == 0) ssq[(size_t)row * 16 + u.pn * 4 + wc] = sq;
; #pragma unroll
;             for (int bj = 0; bj < 2; ++bj) { c16[bj] = n16[bj]; c32[bj][0] = n32[bj][0]; c32[bj][1] = n32[bj][1]; } }
	global_store_dwordx4 v255, v[216:219], s[38:39]
	s_waitcnt lgkmcnt(0)
	global_store_dwordx4 v255, v[242:245], s[4:5]
	v_pk_mul_f32 v[94:95], v[188:189], v[94:95]
	v_pk_mul_f32 v[96:97], v[190:191], v[96:97]
	v_pk_mul_f32 v[90:91], v[184:185], v[90:91]
	v_pk_mul_f32 v[92:93], v[186:187], v[92:93]
	v_pk_mul_f32 v[86:87], v[180:181], v[86:87]
	v_pk_mul_f32 v[88:89], v[182:183], v[88:89]
	v_pk_mul_f32 v[82:83], v[176:177], v[82:83]
	v_pk_mul_f32 v[84:85], v[178:179], v[84:85]
	v_cvt_pk_bf16_f32 v208, v94, v95
	v_cvt_pk_bf16_f32 v209, v96, v97
	v_cvt_pk_bf16_f32 v210, v90, v91
	v_cvt_pk_bf16_f32 v211, v92, v93
	v_cvt_pk_bf16_f32 v212, v86, v87
	v_cvt_pk_bf16_f32 v213, v88, v89
	v_cvt_pk_bf16_f32 v214, v82, v83
	v_cvt_pk_bf16_f32 v215, v84, v85
	v_mov_b32_e32 v82, v246
	ds_write_b128 v250, v[208:211]
	ds_write_b128 v250, v[212:215] offset:64
	ds_read_b128 v[216:219], v251
	ds_read_b128 v[242:245], v251 offset:1024
	s_add_u32 s4, s40, 0x4000
	s_addc_u32 s5, s41, 0
	s_waitcnt lgkmcnt(1)
	global_store_dwordx4 v255, v[216:219], s[40:41]
	s_waitcnt lgkmcnt(0)
	global_store_dwordx4 v255, v[242:245], s[4:5]
	s_add_u32 s38, s38, 0x8000
	s_addc_u32 s39, s39, 0
	s_add_u32 s40, s40, 0x8000
	s_addc_u32 s41, s41, 0
	s_waitcnt vmcnt(20)
	v_pk_fma_f32 v[78:79], v[78:79], v[172:173], v[204:205]
	v_pk_fma_f32 v[80:81], v[80:81], v[174:175], v[206:207]
	v_pk_fma_f32 v[74:75], v[74:75], v[168:169], v[200:201]
	v_pk_fma_f32 v[76:77], v[76:77], v[170:171], v[202:203]
	v_pk_fma_f32 v[70:71], v[70:71], v[164:165], v[196:197]
	v_pk_fma_f32 v[72:73], v[72:73], v[166:167], v[198:199]
	v_pk_fma_f32 v[66:67], v[66:67], v[160:161], v[192:193]
	v_pk_fma_f32 v[68:69], v[68:69], v[162:163], v[194:195]
	global_load_dwordx4 v[204:207], v248, s[36:37]
	global_load_dwordx4 v[200:203], v248, s[36:37] offset:16
	global_load_dwordx4 v[196:199], v248, s[36:37] offset:128
	global_load_dwordx4 v[192:195], v248, s[36:37] offset:144
	s_add_u32 s36, s36, 0x10000
	s_addc_u32 s37, s37, 0
	v_mul_f32_e32 v216, v79, v79
	v_mul_f32_e32 v217, v81, v81
	v_fmac_f32_e32 v216, v78, v78
	v_fmac_f32_e32 v217, v80, v80
	v_add_f32_e32 v216, v216, v217
	v_mul_f32_e32 v217, v75, v75
	v_mul_f32_e32 v218, v77, v77
	v_fmac_f32_e32 v217, v74, v74
	v_fmac_f32_e32 v218, v76, v76
	v_add_f32_e32 v217, v217, v218
	v_add_f32_e32 v216, v216, v217
	v_mul_f32_e32 v217, v71, v71
	v_mul_f32_e32 v218, v73, v73
	v_fmac_f32_e32 v217, v70, v70
	v_fmac_f32_e32 v218, v72, v72
	v_add_f32_e32 v217, v217, v218
	v_mul_f32_e32 v218, v67, v67
	v_mul_f32_e32 v219, v69, v69
	v_fmac_f32_e32 v218, v66, v66
	v_fmac_f32_e32 v219, v68, v68
	v_add_f32_e32 v218, v218, v219
	v_add_f32_e32 v217, v217, v218
	v_add_f32_e32 v246, v216, v217
	v_cvt_pk_bf16_f32 v208, v78, v79
	v_cvt_pk_bf16_f32 v209, v80, v81
	v_cvt_pk_bf16_f32 v210, v74, v75
	v_cvt_pk_bf16_f32 v211, v76, v77
	v_cvt_pk_bf16_f32 v212, v70, v71
	v_cvt_pk_bf16_f32 v213, v72, v73
	v_cvt_pk_bf16_f32 v214, v66, v67
	v_cvt_pk_bf16_f32 v215, v68, v69
	ds_write_b128 v250, v[208:211]
	ds_write_b128 v250, v[212:215] offset:64
	ds_read_b128 v[216:219], v251
	ds_read_b128 v[242:245], v251 offset:1024
	s_add_u32 s4, s38, 0x4000
	s_addc_u32 s5, s39, 0
	s_waitcnt lgkmcnt(1)
	global_store_dwordx4 v255, v[216:219], s[38:39]
	s_waitcnt lgkmcnt(0)
	global_store_dwordx4 v255, v[242:245], s[4:5]
	v_pk_mul_f32 v[78:79], v[188:189], v[78:79]
	v_pk_mul_f32 v[80:81], v[190:191], v[80:81]
	v_pk_mul_f32 v[74:75], v[184:185], v[74:75]
	v_pk_mul_f32 v[76:77], v[186:187], v[76:77]
	v_pk_mul_f32 v[70:71], v[180:181], v[70:71]
	v_pk_mul_f32 v[72:73], v[182:183], v[72:73]
	v_pk_mul_f32 v[66:67], v[176:177], v[66:67]
	v_pk_mul_f32 v[68:69], v[178:179], v[68:69]
	v_cvt_pk_bf16_f32 v208, v78, v79
	v_cvt_pk_bf16_f32 v209, v80, v81
	v_cvt_pk_bf16_f32 v210, v74, v75
	v_cvt_pk_bf16_f32 v211, v76, v77
	v_cvt_pk_bf16_f32 v212, v70, v71
	v_cvt_pk_bf16_f32 v213, v72, v73
	v_cvt_pk_bf16_f32 v214, v66, v67
	v_cvt_pk_bf16_f32 v215, v68, v69
	v_mov_b32_e32 v66, v246
	ds_write_b128 v250, v[208:211]
	ds_write_b128 v250, v[212:215] offset:64
	ds_read_b128 v[216:219], v251
	ds_read_b128 v[242:245], v251 offset:1024
	s_add_u32 s4, s40, 0x4000
	s_addc_u32 s5, s41, 0
	s_waitcnt lgkmcnt(1)
	global_store_dwordx4 v255, v[216:219], s[40:41]
	s_waitcnt lgkmcnt(0)
	global_store_dwordx4 v255, v[242:245], s[4:5]
	s_add_u32 s38, s38, 0x28000
	s_addc_u32 s39, s39, 0
	s_add_u32 s40, s40, 0x28000
	s_addc_u32 s41, s41, 0
	s_waitcnt vmcnt(20)
	v_pk_fma_f32 v[62:63], v[62:63], v[172:173], v[238:239]
	v_pk_fma_f32 v[64:65], v[64:65], v[174:175], v[240:241]
	v_pk_fma_f32 v[58:59], v[58:59], v[168:169], v[234:235]
	v_pk_fma_f32 v[60:61], v[60:61], v[170:171], v[236:237]
	v_pk_fma_f32 v[54:55], v[54:55], v[164:165], v[230:231]
	v_pk_fma_f32 v[56:57], v[56:57], v[166:167], v[232:233]
	v_pk_fma_f32 v[50:51], v[50:51], v[160:161], v[226:227]
	v_pk_fma_f32 v[52:53], v[52:53], v[162:163], v[228:229]
	global_load_dwordx4 v[238:241], v248, s[36:37]
	global_load_dwordx4 v[234:237], v248, s[36:37] offset:16
	global_load_dwordx4 v[230:233], v248, s[36:37] offset:128
	global_load_dwordx4 v[226:229], v248, s[36:37] offset:144
	v_mul_f32_e32 v216, v63, v63
	v_mul_f32_e32 v217, v65, v65
	v_fmac_f32_e32 v216, v62, v62
	v_fmac_f32_e32 v217, v64, v64
	v_add_f32_e32 v216, v216, v217
	v_mul_f32_e32 v217, v59, v59
	v_mul_f32_e32 v218, v61, v61
	v_fmac_f32_e32 v217, v58, v58
	v_fmac_f32_e32 v218, v60, v60
	v_add_f32_e32 v217, v217, v218
	v_add_f32_e32 v216, v216, v217
	v_mul_f32_e32 v217, v55, v55
	v_mul_f32_e32 v218, v57, v57
	v_fmac_f32_e32 v217, v54, v54
	v_fmac_f32_e32 v218, v56, v56
	v_add_f32_e32 v217, v217, v218
	v_mul_f32_e32 v218, v51, v51
	v_mul_f32_e32 v219, v53, v53
	v_fmac_f32_e32 v218, v50, v50
	v_fmac_f32_e32 v219, v52, v52
	v_add_f32_e32 v218, v218, v219
	v_add_f32_e32 v217, v217, v218
	v_add_f32_e32 v246, v216, v217
	v_cvt_pk_bf16_f32 v208, v62, v63
	v_cvt_pk_bf16_f32 v209, v64, v65
	v_cvt_pk_bf16_f32 v210, v58, v59
	v_cvt_pk_bf16_f32 v211, v60, v61
	v_cvt_pk_bf16_f32 v212, v54, v55
	v_cvt_pk_bf16_f32 v213, v56, v57
	v_cvt_pk_bf16_f32 v214, v50, v51
	v_cvt_pk_bf16_f32 v215, v52, v53
	ds_write_b128 v250, v[208:211]
	ds_write_b128 v250, v[212:215] offset:64
	ds_read_b128 v[216:219], v251
	ds_read_b128 v[242:245], v251 offset:1024
	s_add_u32 s4, s38, 0x4000
	s_addc_u32 s5, s39, 0
	s_waitcnt lgkmcnt(1)
; #define PG8_LAS __attribute__((address_space(3)))
; __device__ __forceinline__ u32x4 pack8(const f32x4 a, const f32x4 b) { u32x4 w; w.x = cvt_pk_bf16(a[0], a[1]); w.y = cvt_pk_bf16(a[2], a[3]); w.z = cvt_pk_bf16(b[0], b[1]); w.w = cvt_pk_bf16(b[2], b[3]); return w; }
; __device__ __forceinline__ void store_lines(PG8_LAS unsigned char* stg, const u32x4 P0, const u32x4 P1, int fr, int fq, bf16_t* seg0, int pitch) {
;     const int ln = fq * 16 + fr;
; #pragma unroll
;     for (int h = 0; h < 2; ++h) {
;         if ((fr >> 3) == h) { *(PG8_LAS u32x4*)(stg + (fr & 7) * 128 + fq * 16) = P0; *(PG8_LAS u32x4*)(stg + (fr & 7) * 128 + 64 + fq * 16) = P1; }
;         __builtin_amdgcn_wave_barrier(); asm volatile("" ::: "memory");
;         const u32x4 v = *(const PG8_LAS u32x4*)(stg + ln * 16);
;         __builtin_amdgcn_wave_barrier(); asm volatile("" ::: "memory");
;         *(u32x4*)(seg0 + (size_t)(8 * h + (ln >> 3)) * pitch + (ln & 7) * 8) = v; }
;     __device__ __forceinline__ void operator()(const f32x4 (&acc)[2][2][4][2], const Unit& u, int wr, int wc, int fr, int fq) const {
;     ...
;         for (int r = 0; r < 8; ++r) { const int ai = r >> 2, m = r & 3; const int row = EPI_ROW; float sq = 0.f;
;             if (r < 7) RES_LOAD(n16, n32, r + 1);
;             u32x4 pn_[2], ps_[2];
; #pragma unroll
;             for (int bj = 0; bj < 2; ++bj) {
;                 f32x4 o0, o1;
;                 if (XOLD16) unpack8(c16[bj], o0, o1); else { o0 = c32[bj][0]; o1 = c32[bj][1]; }
;                 const f32x4 v0 = o0 + gv[bj][0] * acc[ai][bj][m][0], v1 = o1 + gv[bj][1] * acc[ai][bj][m][1];
;                 pn_[bj] = pack8(v0, v1);
;                 sq += ((v0[0] * v0[0] + v0[1] * v0[1]) + (v0[2] * v0[2] + v0[3] * v0[3])) + ((v1[0] * v1[0] + v1[1] * v1[1]) + (v1[2] * v1[2] + v1[3] * v1[3]));
;                 if (XS) ps_[bj] = pack8(v0 * cs[bj][0], v1 * cs[bj][1]); }
;             { const size_t seg = (size_t)(row - fr) * DM + u.pn * BM + wc * 64;
;               store_lines(st, pn_[0], pn_[1], fr, fq, xnew + seg, DM);
;               if (XS) store_lines(st, ps_[0], ps_[1], fr, fq, xs + seg, DM); }
	global_store_dwordx4 v255, v[216:219], s[38:39]
	s_waitcnt lgkmcnt(0)
	global_store_dwordx4 v255, v[242:245], s[4:5]
	v_pk_mul_f32 v[62:63], v[188:189], v[62:63]
	v_pk_mul_f32 v[64:65], v[190:191], v[64:65]
	v_pk_mul_f32 v[58:59], v[184:185], v[58:59]
	v_pk_mul_f32 v[60:61], v[186:187], v[60:61]
	v_pk_mul_f32 v[54:55], v[180:181], v[54:55]
	v_pk_mul_f32 v[56:57], v[182:183], v[56:57]
	v_pk_mul_f32 v[50:51], v[176:177], v[50:51]
	v_pk_mul_f32 v[52:53], v[178:179], v[52:53]
	v_cvt_pk_bf16_f32 v208, v62, v63
	v_cvt_pk_bf16_f32 v209, v64, v65
	v_cvt_pk_bf16_f32 v210, v58, v59
	v_cvt_pk_bf16_f32 v211, v60, v61
	v_cvt_pk_bf16_f32 v212, v54, v55
	v_cvt_pk_bf16_f32 v213, v56, v57
	v_cvt_pk_bf16_f32 v214, v50, v51
	v_cvt_pk_bf16_f32 v215, v52, v53
	v_mov_b32_e32 v50, v246
	ds_write_b128 v250, v[208:211]
	ds_write_b128 v250, v[212:215] offset:64
	ds_read_b128 v[216:219], v251
	ds_read_b128 v[242:245], v251 offset:1024
	s_add_u32 s4, s40, 0x4000
	s_addc_u32 s5, s41, 0
	s_waitcnt lgkmcnt(1)
	global_store_dwordx4 v255, v[216:219], s[40:41]
	s_waitcnt lgkmcnt(0)
	global_store_dwordx4 v255, v[242:245], s[4:5]
	s_add_u32 s38, s38, 0x8000
	s_addc_u32 s39, s39, 0
	s_add_u32 s40, s40, 0x8000
	s_addc_u32 s41, s41, 0
	s_waitcnt vmcnt(20)
	v_pk_fma_f32 v[46:47], v[46:47], v[172:173], v[142:143]
	v_pk_fma_f32 v[48:49], v[48:49], v[174:175], v[144:145]
	v_pk_fma_f32 v[42:43], v[42:43], v[168:169], v[138:139]
	v_pk_fma_f32 v[44:45], v[44:45], v[170:171], v[140:141]
	v_pk_fma_f32 v[38:39], v[38:39], v[164:165], v[134:135]
	v_pk_fma_f32 v[40:41], v[40:41], v[166:167], v[136:137]
	v_pk_fma_f32 v[34:35], v[34:35], v[160:161], v[130:131]
	v_pk_fma_f32 v[36:37], v[36:37], v[162:163], v[132:133]
	v_mul_f32_e32 v216, v47, v47
	v_mul_f32_e32 v217, v49, v49
	v_fmac_f32_e32 v216, v46, v46
	v_fmac_f32_e32 v217, v48, v48
	v_add_f32_e32 v216, v216, v217
	v_mul_f32_e32 v217, v43, v43
	v_mul_f32_e32 v218, v45, v45
	v_fmac_f32_e32 v217, v42, v42
	v_fmac_f32_e32 v218, v44, v44
	v_add_f32_e32 v217, v217, v218
	v_add_f32_e32 v216, v216, v217
	v_mul_f32_e32 v217, v39, v39
	v_mul_f32_e32 v218, v41, v41
	v_fmac_f32_e32 v217, v38, v38
	v_fmac_f32_e32 v218, v40, v40
	v_add_f32_e32 v217, v217, v218
	v_mul_f32_e32 v218, v35, v35
	v_mul_f32_e32 v219, v37, v37
	v_fmac_f32_e32 v218, v34, v34
	v_fmac_f32_e32 v219, v36, v36
	v_add_f32_e32 v218, v218, v219
	v_add_f32_e32 v217, v217, v218
	v_add_f32_e32 v246, v216, v217
	v_cvt_pk_bf16_f32 v208, v46, v47
	v_cvt_pk_bf16_f32 v209, v48, v49
	v_cvt_pk_bf16_f32 v210, v42, v43
	v_cvt_pk_bf16_f32 v211, v44, v45
	v_cvt_pk_bf16_f32 v212, v38, v39
	v_cvt_pk_bf16_f32 v213, v40, v41
	v_cvt_pk_bf16_f32 v214, v34, v35
	v_cvt_pk_bf16_f32 v215, v36, v37
	ds_write_b128 v250, v[208:211]
	ds_write_b128 v250, v[212:215] offset:64
	ds_read_b128 v[216:219], v251
	ds_read_b128 v[242:245], v251 offset:1024
	s_add_u32 s4, s38, 0x4000
	s_addc_u32 s5, s39, 0
	s_waitcnt lgkmcnt(1)
	global_store_dwordx4 v255, v[216:219], s[38:39]
	s_waitcnt lgkmcnt(0)
	global_store_dwordx4 v255, v[242:245], s[4:5]
	v_pk_mul_f32 v[46:47], v[188:189], v[46:47]
	v_pk_mul_f32 v[48:49], v[190:191], v[48:49]
	v_pk_mul_f32 v[42:43], v[184:185], v[42:43]
	v_pk_mul_f32 v[44:45], v[186:187], v[44:45]
	v_pk_mul_f32 v[38:39], v[180:181], v[38:39]
	v_pk_mul_f32 v[40:41], v[182:183], v[40:41]
	v_pk_mul_f32 v[34:35], v[176:177], v[34:35]
	v_pk_mul_f32 v[36:37], v[178:179], v[36:37]
	v_cvt_pk_bf16_f32 v208, v46, v47
	v_cvt_pk_bf16_f32 v209, v48, v49
	v_cvt_pk_bf16_f32 v210, v42, v43
	v_cvt_pk_bf16_f32 v211, v44, v45
	v_cvt_pk_bf16_f32 v212, v38, v39
	v_cvt_pk_bf16_f32 v213, v40, v41
	v_cvt_pk_bf16_f32 v214, v34, v35
	v_cvt_pk_bf16_f32 v215, v36, v37
	v_mov_b32_e32 v34, v246
	ds_write_b128 v250, v[208:211]
	ds_write_b128 v250, v[212:215] offset:64
	ds_read_b128 v[216:219], v251
	ds_read_b128 v[242:245], v251 offset:1024
	s_add_u32 s4, s40, 0x4000
	s_addc_u32 s5, s41, 0
	s_waitcnt lgkmcnt(1)
	global_store_dwordx4 v255, v[216:219], s[40:41]
	s_waitcnt lgkmcnt(0)
	global_store_dwordx4 v255, v[242:245], s[4:5]
	s_add_u32 s38, s38, 0x8000
	s_addc_u32 s39, s39, 0
	s_add_u32 s40, s40, 0x8000
	s_addc_u32 s41, s41, 0
	s_waitcnt vmcnt(16)
	v_pk_fma_f32 v[30:31], v[30:31], v[172:173], v[204:205]
	v_pk_fma_f32 v[32:33], v[32:33], v[174:175], v[206:207]
	v_pk_fma_f32 v[26:27], v[26:27], v[168:169], v[200:201]
	v_pk_fma_f32 v[28:29], v[28:29], v[170:171], v[202:203]
	v_pk_fma_f32 v[22:23], v[22:23], v[164:165], v[196:197]
	v_pk_fma_f32 v[24:25], v[24:25], v[166:167], v[198:199]
	v_pk_fma_f32 v[18:19], v[18:19], v[160:161], v[192:193]
	v_pk_fma_f32 v[20:21], v[20:21], v[162:163], v[194:195]
	v_mul_f32_e32 v216, v31, v31
	v_mul_f32_e32 v217, v33, v33
	v_fmac_f32_e32 v216, v30, v30
	v_fmac_f32_e32 v217, v32, v32
	v_add_f32_e32 v216, v216, v217
	v_mul_f32_e32 v217, v27, v27
	v_mul_f32_e32 v218, v29, v29
	v_fmac_f32_e32 v217, v26, v26
	v_fmac_f32_e32 v218, v28, v28
	v_add_f32_e32 v217, v217, v218
	v_add_f32_e32 v216, v216, v217
	v_mul_f32_e32 v217, v23, v23
	v_mul_f32_e32 v218, v25, v25
	v_fmac_f32_e32 v217, v22, v22
	v_fmac_f32_e32 v218, v24, v24
	v_add_f32_e32 v217, v217, v218
	v_mul_f32_e32 v218, v19, v19
	v_mul_f32_e32 v219, v21, v21
	v_fmac_f32_e32 v218, v18, v18
	v_fmac_f32_e32 v219, v20, v20
	v_add_f32_e32 v218, v218, v219
	v_add_f32_e32 v217, v217, v218
	v_add_f32_e32 v246, v216, v217
	v_cvt_pk_bf16_f32 v208, v30, v31
	v_cvt_pk_bf16_f32 v209, v32, v33
	v_cvt_pk_bf16_f32 v210, v26, v27
	v_cvt_pk_bf16_f32 v211, v28, v29
	v_cvt_pk_bf16_f32 v212, v22, v23
	v_cvt_pk_bf16_f32 v213, v24, v25
	v_cvt_pk_bf16_f32 v214, v18, v19
	v_cvt_pk_bf16_f32 v215, v20, v21
	ds_write_b128 v250, v[208:211]
	ds_write_b128 v250, v[212:215] offset:64
	ds_read_b128 v[216:219], v251
	ds_read_b128 v[242:245], v251 offset:1024
	s_add_u32 s4, s38, 0x4000
	s_addc_u32 s5, s39, 0
	s_waitcnt lgkmcnt(1)
; #define PG8_LAS __attribute__((address_space(3)))
; __device__ __forceinline__ u32x4 pack8(const f32x4 a, const f32x4 b) { u32x4 w; w.x = cvt_pk_bf16(a[0], a[1]); w.y = cvt_pk_bf16(a[2], a[3]); w.z = cvt_pk_bf16(b[0], b[1]); w.w = cvt_pk_bf16(b[2], b[3]); return w; }
; __device__ __forceinline__ void store_lines(PG8_LAS unsigned char* stg, const u32x4 P0, const u32x4 P1, int fr, int fq, bf16_t* seg0, int pitch) {
;     const int ln = fq * 16 + fr;
; #pragma unroll
;     for (int h = 0; h < 2; ++h) {
;         if ((fr >> 3) == h) { *(PG8_LAS u32x4*)(stg + (fr & 7) * 128 + fq * 16) = P0; *(PG8_LAS u32x4*)(stg + (fr & 7) * 128 + 64 + fq * 16) = P1; }
;         __builtin_amdgcn_wave_barrier(); asm volatile("" ::: "memory");
;         const u32x4 v = *(const PG8_LAS u32x4*)(stg + ln * 16);
;         __builtin_amdgcn_wave_barrier(); asm volatile("" ::: "memory");
;         *(u32x4*)(seg0 + (size_t)(8 * h + (ln >> 3)) * pitch + (ln & 7) * 8) = v; }
;     __device__ __forceinline__ void operator()(const f32x4 (&acc)[2][2][4][2], const Unit& u, int wr, int wc, int fr, int fq) const {
;     ...
;         for (int r = 0; r < 8; ++r) { const int ai = r >> 2, m = r & 3; const int row = EPI_ROW; float sq = 0.f;
;             if (r < 7) RES_LOAD(n16, n32, r + 1);
;             u32x4 pn_[2], ps_[2];
; #pragma unroll
;             for (int bj = 0; bj < 2; ++bj) {
;                 f32x4 o0, o1;
;                 if (XOLD16) unpack8(c16[bj], o0, o1); else { o0 = c32[bj][0]; o1 = c32[bj][1]; }
;                 const f32x4 v0 = o0 + gv[bj][0] * acc[ai][bj][m][0], v1 = o1 + gv[bj][1] * acc[ai][bj][m][1];
;                 pn_[bj] = pack8(v0, v1);
;                 sq += ((v0[0] * v0[0] + v0[1] * v0[1]) + (v0[2] * v0[2] + v0[3] * v0[3])) + ((v1[0] * v1[0] + v1[1] * v1[1]) + (v1[2] * v1[2] + v1[3] * v1[3]));
;                 if (XS) ps_[bj] = pack8(v0 * cs[bj][0], v1 * cs[bj][1]); }
;             { const size_t seg = (size_t)(row - fr) * DM + u.pn * BM + wc * 64;
;               store_lines(st, pn_[0], pn_[1], fr, fq, xnew + seg, DM);
;               if (XS) store_lines(st, ps_[0], ps_[1], fr, fq, xs + seg, DM); }
;             sq += __shfl_xor(sq, 16); sq += __shfl_xor(sq, 32);
;             if (fq == 0) ssq[(size_t)row * 16 + u.pn * 4 + wc] = sq;
; #pragma unroll
;             for (int bj = 0; bj < 2; ++bj) { c16[bj] = n16[bj]; c32[bj][0] = n32[bj][0]; c32[bj][1] = n32[bj][1]; } }
	global_store_dwordx4 v255, v[216:219], s[38:39]
	s_waitcnt lgkmcnt(0)
	global_store_dwordx4 v255, v[242:245], s[4:5]
	v_pk_mul_f32 v[30:31], v[188:189], v[30:31]
	v_pk_mul_f32 v[32:33], v[190:191], v[32:33]
	v_pk_mul_f32 v[26:27], v[184:185], v[26:27]
	v_pk_mul_f32 v[28:29], v[186:187], v[28:29]
	v_pk_mul_f32 v[22:23], v[180:181], v[22:23]
	v_pk_mul_f32 v[24:25], v[182:183], v[24:25]
	v_pk_mul_f32 v[18:19], v[176:177], v[18:19]
	v_pk_mul_f32 v[20:21], v[178:179], v[20:21]
	v_cvt_pk_bf16_f32 v208, v30, v31
	v_cvt_pk_bf16_f32 v209, v32, v33
	v_cvt_pk_bf16_f32 v210, v26, v27
	v_cvt_pk_bf16_f32 v211, v28, v29
	v_cvt_pk_bf16_f32 v212, v22, v23
	v_cvt_pk_bf16_f32 v213, v24, v25
	v_cvt_pk_bf16_f32 v214, v18, v19
	v_cvt_pk_bf16_f32 v215, v20, v21
	v_mov_b32_e32 v18, v246
	ds_write_b128 v250, v[208:211]
	ds_write_b128 v250, v[212:215] offset:64
	ds_read_b128 v[216:219], v251
	ds_read_b128 v[242:245], v251 offset:1024
	s_add_u32 s4, s40, 0x4000
	s_addc_u32 s5, s41, 0
	s_waitcnt lgkmcnt(1)
	global_store_dwordx4 v255, v[216:219], s[40:41]
	s_waitcnt lgkmcnt(0)
	global_store_dwordx4 v255, v[242:245], s[4:5]
	s_add_u32 s38, s38, 0x8000
	s_addc_u32 s39, s39, 0
	s_add_u32 s40, s40, 0x8000
	s_addc_u32 s41, s41, 0
	s_waitcnt vmcnt(12)
	v_pk_fma_f32 v[14:15], v[14:15], v[172:173], v[238:239]
	v_pk_fma_f32 v[16:17], v[16:17], v[174:175], v[240:241]
	v_pk_fma_f32 v[10:11], v[10:11], v[168:169], v[234:235]
	v_pk_fma_f32 v[12:13], v[12:13], v[170:171], v[236:237]
	v_pk_fma_f32 v[6:7], v[6:7], v[164:165], v[230:231]
	v_pk_fma_f32 v[8:9], v[8:9], v[166:167], v[232:233]
	v_pk_fma_f32 v[2:3], v[2:3], v[160:161], v[226:227]
	v_pk_fma_f32 v[4:5], v[4:5], v[162:163], v[228:229]
	v_mul_f32_e32 v216, v15, v15
	v_mul_f32_e32 v217, v17, v17
	v_fmac_f32_e32 v216, v14, v14
	v_fmac_f32_e32 v217, v16, v16
	v_add_f32_e32 v216, v216, v217
	v_mul_f32_e32 v217, v11, v11
	v_mul_f32_e32 v218, v13, v13
	v_fmac_f32_e32 v217, v10, v10
	v_fmac_f32_e32 v218, v12, v12
	v_add_f32_e32 v217, v217, v218
	v_add_f32_e32 v216, v216, v217
	v_mul_f32_e32 v217, v7, v7
	v_mul_f32_e32 v218, v9, v9
	v_fmac_f32_e32 v217, v6, v6
	v_fmac_f32_e32 v218, v8, v8
	v_add_f32_e32 v217, v217, v218
	v_mul_f32_e32 v218, v3, v3
	v_mul_f32_e32 v219, v5, v5
	v_fmac_f32_e32 v218, v2, v2
	v_fmac_f32_e32 v219, v4, v4
	v_add_f32_e32 v218, v218, v219
	v_add_f32_e32 v217, v217, v218
	v_add_f32_e32 v246, v216, v217
	v_cvt_pk_bf16_f32 v208, v14, v15
	v_cvt_pk_bf16_f32 v209, v16, v17
	v_cvt_pk_bf16_f32 v210, v10, v11
	v_cvt_pk_bf16_f32 v211, v12, v13
	v_cvt_pk_bf16_f32 v212, v6, v7
	v_cvt_pk_bf16_f32 v213, v8, v9
	v_cvt_pk_bf16_f32 v214, v2, v3
	v_cvt_pk_bf16_f32 v215, v4, v5
	ds_write_b128 v250, v[208:211]
	ds_write_b128 v250, v[212:215] offset:64
	ds_read_b128 v[216:219], v251
	ds_read_b128 v[242:245], v251 offset:1024
	s_add_u32 s4, s38, 0x4000
	s_addc_u32 s5, s39, 0
	s_waitcnt lgkmcnt(1)
	global_store_dwordx4 v255, v[216:219], s[38:39]
	s_waitcnt lgkmcnt(0)
	global_store_dwordx4 v255, v[242:245], s[4:5]
	v_pk_mul_f32 v[14:15], v[188:189], v[14:15]
	v_pk_mul_f32 v[16:17], v[190:191], v[16:17]
	v_pk_mul_f32 v[10:11], v[184:185], v[10:11]
	v_pk_mul_f32 v[12:13], v[186:187], v[12:13]
	v_pk_mul_f32 v[6:7], v[180:181], v[6:7]
	v_pk_mul_f32 v[8:9], v[182:183], v[8:9]
	v_pk_mul_f32 v[2:3], v[176:177], v[2:3]
	v_pk_mul_f32 v[4:5], v[178:179], v[4:5]
	v_cvt_pk_bf16_f32 v208, v14, v15
	v_cvt_pk_bf16_f32 v209, v16, v17
	v_cvt_pk_bf16_f32 v210, v10, v11
	v_cvt_pk_bf16_f32 v211, v12, v13
	v_cvt_pk_bf16_f32 v212, v6, v7
	v_cvt_pk_bf16_f32 v213, v8, v9
	v_cvt_pk_bf16_f32 v214, v2, v3
	v_cvt_pk_bf16_f32 v215, v4, v5
	v_mov_b32_e32 v2, v246
	ds_write_b128 v250, v[208:211]
	ds_write_b128 v250, v[212:215] offset:64
	ds_read_b128 v[216:219], v251
	ds_read_b128 v[242:245], v251 offset:1024
	s_add_u32 s4, s40, 0x4000
	s_addc_u32 s5, s41, 0
	s_waitcnt lgkmcnt(1)
	global_store_dwordx4 v255, v[216:219], s[40:41]
	s_waitcnt lgkmcnt(0)
	global_store_dwordx4 v255, v[242:245], s[4:5]
	v_xor_b32_e32 v216, 16, v220
	v_xor_b32_e32 v217, 32, v220
	v_lshlrev_b32_e32 v216, 2, v216
	v_lshlrev_b32_e32 v217, 2, v217
	ds_bpermute_b32 v208, v216, v114
	ds_bpermute_b32 v209, v216, v98
	ds_bpermute_b32 v210, v216, v82
	ds_bpermute_b32 v211, v216, v66
	ds_bpermute_b32 v212, v216, v50
	ds_bpermute_b32 v213, v216, v34
	ds_bpermute_b32 v214, v216, v18
	ds_bpermute_b32 v215, v216, v2
	s_waitcnt lgkmcnt(0)
	v_add_f32_e32 v114, v114, v208
	v_add_f32_e32 v98, v98, v209
	v_add_f32_e32 v82, v82, v210
	v_add_f32_e32 v66, v66, v211
	v_add_f32_e32 v50, v50, v212
	v_add_f32_e32 v34, v34, v213
	v_add_f32_e32 v18, v18, v214
	v_add_f32_e32 v2, v2, v215
	ds_bpermute_b32 v208, v217, v114
	ds_bpermute_b32 v209, v217, v98
	ds_bpermute_b32 v210, v217, v82
	ds_bpermute_b32 v211, v217, v66
	ds_bpermute_b32 v212, v217, v50
	ds_bpermute_b32 v213, v217, v34
	ds_bpermute_b32 v214, v217, v18
	ds_bpermute_b32 v215, v217, v2
	s_waitcnt lgkmcnt(0)
	v_add_f32_e32 v114, v114, v208
	v_add_f32_e32 v98, v98, v209
	v_add_f32_e32 v82, v82, v210
	v_add_f32_e32 v66, v66, v211
	v_add_f32_e32 v50, v50, v212
	v_add_f32_e32 v34, v34, v213
	v_add_f32_e32 v18, v18, v214
	v_add_f32_e32 v2, v2, v215
	s_lshl_b32 s4, s98, 8
	s_add_i32 s4, s4, s62
	s_lshl_b32 s4, s4, 6
	s_lshl_b32 s5, s16, 4
	s_add_u32 s4, s4, s5
	s_lshl_b32 s5, s61, 2
	s_add_u32 s4, s4, s5
	s_add_u32 s36, s20, s4
	s_addc_u32 s37, s21, 0
	s_add_u32 s38, s36, 0x2000
	s_addc_u32 s39, s37, 0
	s_mov_b64 exec, 0xffff
	global_store_dword v249, v114, s[36:37] offset:0
	global_store_dword v249, v98, s[36:37] offset:1024
	global_store_dword v249, v82, s[36:37] offset:2048
	global_store_dword v249, v66, s[36:37] offset:3072
	global_store_dword v249, v50, s[38:39] offset:0
	global_store_dword v249, v34, s[38:39] offset:1024
	global_store_dword v249, v18, s[38:39] offset:2048
	global_store_dword v249, v2, s[38:39] offset:3072
	s_mov_b64 exec, -1
	s_and_b64 vcc, exec, s[2:3]
	s_mov_b64 s[0:1], -1
	s_cbranch_vccnz .LBB0_277
	s_andn2_b64 vcc, exec, s[18:19]
	s_cbranch_vccnz .LBB0_276
	s_barrier
	s_branch .LBB0_276
